# write-through (sc1) on the P6 epilogue x1 stores
# baseline (speedup 1.0000x reference)
.LBB0_766:
	s_add_u32 s17, s10, 0x2000000
	s_addc_u32 s18, s11, 0
	s_add_u32 s15, s10, 0x1000000
	s_addc_u32 s16, s11, 0
	s_lshl_b32 s4, s47, 5
	s_barrier
	v_mbcnt_lo_u32_b32 v133, -1, 0
	v_mbcnt_hi_u32_b32 v133, -1, v133
	s_lshl_b32 s30, s33, 3
	v_and_or_b32 v132, v133, 15, s4
	s_lshl_b32 s4, s33, 4
	s_andn2_b32 s4, s4, 63
	s_lshl_b32 s6, s14, 8
	s_and_b32 s5, s30, 16
	s_add_i32 s6, s6, s4
	s_or_b32 s31, s6, s5
	s_movk_i32 s6, 0x410
	s_lshl_b32 s4, s8, 8
	v_mul_lo_u32 v132, v132, s6
	s_lshl_b32 s6, s49, 7
	s_ashr_i32 s5, s4, 31
	s_add_i32 s6, s6, 0
	s_and_b32 s19, s30, 8
	s_ashr_i32 s9, s8, 31
	v_lshlrev_b32_e32 v134, 1, v133
	v_add_u32_e32 v132, s6, v132
	s_lshl_b64 s[6:7], s[4:5], 2
	v_lshlrev_b32_e32 v130, 2, v133
	v_and_b32_e32 v134, 0xffffffe0, v134
	s_add_u32 s6, s12, s6
	v_ashrrev_i32_e32 v131, 31, v130
	v_add_u32_e32 v132, v132, v134
	s_addc_u32 s7, s13, s7
	ds_write_b128 v132, v[126:129]
	ds_write_b128 v132, v[122:125] offset:16
	ds_write_b128 v132, v[110:113] offset:512
	ds_write_b128 v132, v[106:109] offset:528
	ds_write_b128 v132, v[118:121] offset:16640
	ds_write_b128 v132, v[114:117] offset:16656
	ds_write_b128 v132, v[102:105] offset:17152
	ds_write_b128 v132, v[98:101] offset:17168
	v_lshl_add_u64 v[126:127], v[130:131], 2, s[6:7]
	s_or_b32 s6, s31, s19
	s_ashr_i32 s7, s6, 31
	s_lshl_b64 s[10:11], s[6:7], 12
	s_or_b32 s12, s19, 1
	v_lshl_add_u64 v[98:99], v[126:127], 0, s[10:11]
	s_or_b32 s10, s31, s12
	s_ashr_i32 s11, s10, 31
	s_lshl_b64 s[10:11], s[10:11], 12
	s_or_b32 s13, s19, 2
	v_lshl_add_u64 v[100:101], v[126:127], 0, s[10:11]
	s_or_b32 s10, s31, s13
	s_ashr_i32 s11, s10, 31
	s_lshl_b64 s[10:11], s[10:11], 12
	s_or_b32 s14, s19, 3
	s_waitcnt vmcnt(0) lgkmcnt(0)
	s_barrier
	global_load_dwordx4 v[134:137], v[98:99], off
	global_load_dwordx4 v[122:125], v[100:101], off
	v_lshl_add_u64 v[98:99], v[126:127], 0, s[10:11]
	s_or_b32 s10, s31, s14
	s_ashr_i32 s11, s10, 31
	s_lshl_b64 s[10:11], s[10:11], 12
	s_or_b32 s20, s19, 4
	v_lshl_add_u64 v[100:101], v[126:127], 0, s[10:11]
	s_or_b32 s10, s31, s20
	s_ashr_i32 s11, s10, 31
	s_lshl_b64 s[10:11], s[10:11], 12
	s_or_b32 s22, s19, 5
	global_load_dwordx4 v[118:121], v[98:99], off
	global_load_dwordx4 v[114:117], v[100:101], off
	v_lshl_add_u64 v[98:99], v[126:127], 0, s[10:11]
	s_or_b32 s10, s31, s22
	s_ashr_i32 s11, s10, 31
	s_lshl_b64 s[10:11], s[10:11], 12
	s_or_b32 s21, s19, 6
	v_lshl_add_u64 v[100:101], v[126:127], 0, s[10:11]
	s_or_b32 s10, s31, s21
	s_ashr_i32 s11, s10, 31
	s_lshl_b64 s[10:11], s[10:11], 12
	s_or_b32 s23, s19, 7
	global_load_dwordx4 v[110:113], v[98:99], off
	global_load_dwordx4 v[106:109], v[100:101], off
	v_lshl_add_u64 v[98:99], v[126:127], 0, s[10:11]
	s_or_b32 s10, s31, s23
	s_ashr_i32 s11, s10, 31
	s_lshl_b64 s[10:11], s[10:11], 12
	v_lshl_add_u64 v[100:101], v[126:127], 0, s[10:11]
	global_load_dwordx4 v[102:105], v[98:99], off
	s_nop 0
	global_load_dwordx4 v[98:101], v[100:101], off
	v_lshl_add_u32 v128, v133, 4, 0
	s_mulk_i32 s33, 0x2080
	v_add_u32_e32 v129, s33, v128
	ds_read_b128 v[138:141], v129
	v_cmp_eq_u32_e32 vcc, 0, v133
	s_lshl_b64 s[10:11], s[6:7], 11
	s_add_u32 s10, s17, s10
	s_addc_u32 s11, s18, s11
	s_lshl_b64 s[4:5], s[4:5], 1
	s_add_u32 s10, s10, s4
	s_addc_u32 s11, s11, s5
	s_waitcnt vmcnt(7) lgkmcnt(0)
	v_pk_add_f32 v[134:135], v[134:135], v[138:139]
	v_pk_add_f32 v[136:137], v[136:137], v[140:141]
	v_mul_f32_e32 v133, v135, v135
	v_cvt_pk_bf16_f32 v138, v134, v135
	v_fmac_f32_e32 v133, v134, v134
	v_mul_f32_e32 v134, v137, v137
	v_fmac_f32_e32 v134, v136, v136
	v_add_f32_e32 v133, v133, v134
	v_cvt_pk_bf16_f32 v139, v136, v137
	v_lshl_add_u64 v[140:141], v[130:131], 1, s[10:11]
	v_add_f32_dpp v133, v133, v133 quad_perm:[1,0,3,2] row_mask:0xf bank_mask:0xf bound_ctrl:1
	global_store_dwordx2 v[140:141], v[138:139], off sc1
	s_nop 0
	v_add_f32_dpp v133, v133, v133 quad_perm:[2,3,0,1] row_mask:0xf bank_mask:0xf bound_ctrl:1
	s_nop 1
	v_add_f32_dpp v133, v133, v133 row_half_mirror row_mask:0xf bank_mask:0xf bound_ctrl:1
	s_nop 1
	v_add_f32_dpp v133, v133, v133 row_mirror row_mask:0xf bank_mask:0xf bound_ctrl:1
	v_mov_b32_e32 v134, v133
	s_nop 1
	v_permlane16_swap_b32_e32 v133, v134
	v_add_f32_e32 v133, v133, v134
	v_mov_b32_e32 v134, v133
	s_nop 1
	v_permlane32_swap_b32_e32 v133, v134
	s_and_saveexec_b64 s[10:11], vcc
	s_cbranch_execz .LBB0_768
	s_lshl_b64 s[6:7], s[6:7], 4
	s_add_u32 s24, s15, s6
	s_addc_u32 s25, s16, s7
	s_lshl_b64 s[6:7], s[8:9], 2
	s_add_u32 s6, s24, s6
	s_addc_u32 s7, s25, s7
	v_mov_b32_e32 v135, 0
	v_add_f32_e32 v133, v133, v134
	global_store_dword v135, v133, s[6:7]
.LBB0_768:
	s_or_b64 exec, exec, s[10:11]
	s_or_b32 s6, s30, 1
	s_mul_i32 s7, s6, 0x410
	v_add_u32_e32 v128, s7, v128
	ds_read_b128 v[134:137], v128
	s_and_b32 s24, s6, 9
	s_or_b32 s6, s31, s24
	s_ashr_i32 s7, s6, 31
	s_lshl_b64 s[10:11], s[6:7], 11
	s_waitcnt vmcnt(7) lgkmcnt(0)
	v_pk_add_f32 v[122:123], v[122:123], v[134:135]
	v_pk_add_f32 v[124:125], v[124:125], v[136:137]
	v_cvt_pk_bf16_f32 v134, v122, v123
	v_mul_f32_e32 v123, v123, v123
	v_fmac_f32_e32 v123, v122, v122
	v_mul_f32_e32 v122, v125, v125
	v_fmac_f32_e32 v122, v124, v124
	v_add_f32_e32 v122, v123, v122
	s_add_u32 s10, s17, s10
	s_addc_u32 s11, s18, s11
	v_add_f32_dpp v122, v122, v122 quad_perm:[1,0,3,2] row_mask:0xf bank_mask:0xf bound_ctrl:1
	s_add_u32 s10, s10, s4
	s_addc_u32 s11, s11, s5
	v_add_f32_dpp v122, v122, v122 quad_perm:[2,3,0,1] row_mask:0xf bank_mask:0xf bound_ctrl:1
	v_cvt_pk_bf16_f32 v135, v124, v125
	v_lshl_add_u64 v[136:137], v[130:131], 1, s[10:11]
	v_add_f32_dpp v122, v122, v122 row_half_mirror row_mask:0xf bank_mask:0xf bound_ctrl:1
	global_store_dwordx2 v[136:137], v[134:135], off sc1
	s_nop 0
	v_add_f32_dpp v122, v122, v122 row_mirror row_mask:0xf bank_mask:0xf bound_ctrl:1
	v_mov_b32_e32 v123, v122
	s_nop 1
	v_permlane16_swap_b32_e32 v122, v123
	v_add_f32_e32 v122, v122, v123
	v_mov_b32_e32 v123, v122
	s_nop 1
	v_permlane32_swap_b32_e32 v122, v123
	s_and_saveexec_b64 s[10:11], vcc
	s_cbranch_execz .LBB0_770
	s_lshl_b64 s[6:7], s[6:7], 4
	s_add_u32 s25, s15, s6
	s_addc_u32 s26, s16, s7
	s_lshl_b64 s[6:7], s[8:9], 2
	s_add_u32 s6, s25, s6
	s_addc_u32 s7, s26, s7
	v_mov_b32_e32 v124, 0
	v_add_f32_e32 v122, v122, v123
	global_store_dword v124, v122, s[6:7]
.LBB0_770:
	s_or_b64 exec, exec, s[10:11]
	ds_read_b128 v[122:125], v128 offset:1040
	s_or_b32 s6, s30, 2
	s_and_b32 s25, s6, 10
	s_or_b32 s6, s31, s25
	s_ashr_i32 s7, s6, 31
	s_waitcnt vmcnt(7) lgkmcnt(0)
	v_pk_add_f32 v[118:119], v[118:119], v[122:123]
	v_pk_add_f32 v[120:121], v[120:121], v[124:125]
	v_cvt_pk_bf16_f32 v122, v118, v119
	v_mul_f32_e32 v119, v119, v119
	v_fmac_f32_e32 v119, v118, v118
	v_mul_f32_e32 v118, v121, v121
	v_fmac_f32_e32 v118, v120, v120
	v_add_f32_e32 v118, v119, v118
	s_lshl_b64 s[10:11], s[6:7], 11
	s_add_u32 s10, s17, s10
	v_add_f32_dpp v118, v118, v118 quad_perm:[1,0,3,2] row_mask:0xf bank_mask:0xf bound_ctrl:1
	s_addc_u32 s11, s18, s11
	s_add_u32 s10, s10, s4
	v_add_f32_dpp v118, v118, v118 quad_perm:[2,3,0,1] row_mask:0xf bank_mask:0xf bound_ctrl:1
	s_addc_u32 s11, s11, s5
	v_cvt_pk_bf16_f32 v123, v120, v121
	v_add_f32_dpp v118, v118, v118 row_half_mirror row_mask:0xf bank_mask:0xf bound_ctrl:1
	v_lshl_add_u64 v[124:125], v[130:131], 1, s[10:11]
	global_store_dwordx2 v[124:125], v[122:123], off sc1
	v_add_f32_dpp v118, v118, v118 row_mirror row_mask:0xf bank_mask:0xf bound_ctrl:1
	v_mov_b32_e32 v119, v118
	s_nop 1
	v_permlane16_swap_b32_e32 v118, v119
	v_add_f32_e32 v118, v118, v119
	v_mov_b32_e32 v119, v118
	s_nop 1
	v_permlane32_swap_b32_e32 v118, v119
	s_and_saveexec_b64 s[10:11], vcc
	s_cbranch_execz .LBB0_772
	s_lshl_b64 s[6:7], s[6:7], 4
	s_add_u32 s26, s15, s6
	s_addc_u32 s27, s16, s7
	s_lshl_b64 s[6:7], s[8:9], 2
	s_add_u32 s6, s26, s6
	s_addc_u32 s7, s27, s7
	v_mov_b32_e32 v120, 0
	v_add_f32_e32 v118, v118, v119
	global_store_dword v120, v118, s[6:7]
.LBB0_772:
	s_or_b64 exec, exec, s[10:11]
	ds_read_b128 v[118:121], v128 offset:2080
	s_or_b32 s6, s30, 3
	s_and_b32 s26, s6, 11
	s_or_b32 s6, s31, s26
	s_ashr_i32 s7, s6, 31
	s_waitcnt vmcnt(7) lgkmcnt(0)
	v_pk_add_f32 v[114:115], v[114:115], v[118:119]
	v_pk_add_f32 v[116:117], v[116:117], v[120:121]
	v_cvt_pk_bf16_f32 v118, v114, v115
	v_mul_f32_e32 v115, v115, v115
	v_fmac_f32_e32 v115, v114, v114
	v_mul_f32_e32 v114, v117, v117
	v_fmac_f32_e32 v114, v116, v116
	v_add_f32_e32 v114, v115, v114
	s_lshl_b64 s[10:11], s[6:7], 11
	s_add_u32 s10, s17, s10
	v_add_f32_dpp v114, v114, v114 quad_perm:[1,0,3,2] row_mask:0xf bank_mask:0xf bound_ctrl:1
	s_addc_u32 s11, s18, s11
	s_add_u32 s10, s10, s4
	v_add_f32_dpp v114, v114, v114 quad_perm:[2,3,0,1] row_mask:0xf bank_mask:0xf bound_ctrl:1
	s_addc_u32 s11, s11, s5
	v_cvt_pk_bf16_f32 v119, v116, v117
	v_add_f32_dpp v114, v114, v114 row_half_mirror row_mask:0xf bank_mask:0xf bound_ctrl:1
	v_lshl_add_u64 v[120:121], v[130:131], 1, s[10:11]
	global_store_dwordx2 v[120:121], v[118:119], off sc1
	v_add_f32_dpp v114, v114, v114 row_mirror row_mask:0xf bank_mask:0xf bound_ctrl:1
	v_mov_b32_e32 v115, v114
	s_nop 1
	v_permlane16_swap_b32_e32 v114, v115
	v_add_f32_e32 v114, v114, v115
	v_mov_b32_e32 v115, v114
	s_nop 1
	v_permlane32_swap_b32_e32 v114, v115
	s_and_saveexec_b64 s[10:11], vcc
	s_cbranch_execz .LBB0_774
	s_lshl_b64 s[6:7], s[6:7], 4
	s_add_u32 s27, s15, s6
	s_addc_u32 s28, s16, s7
	s_lshl_b64 s[6:7], s[8:9], 2
	s_add_u32 s6, s27, s6
	s_addc_u32 s7, s28, s7
	v_mov_b32_e32 v116, 0
	v_add_f32_e32 v114, v114, v115
	global_store_dword v116, v114, s[6:7]
.LBB0_774:
	s_or_b64 exec, exec, s[10:11]
	ds_read_b128 v[114:117], v128 offset:3120
	s_or_b32 s6, s30, 4
	s_and_b32 s27, s6, 12
	s_or_b32 s6, s31, s27
	s_ashr_i32 s7, s6, 31
	s_waitcnt vmcnt(7) lgkmcnt(0)
	v_pk_add_f32 v[110:111], v[110:111], v[114:115]
	v_pk_add_f32 v[112:113], v[112:113], v[116:117]
	v_cvt_pk_bf16_f32 v114, v110, v111
	v_mul_f32_e32 v111, v111, v111
	v_fmac_f32_e32 v111, v110, v110
	v_mul_f32_e32 v110, v113, v113
	v_fmac_f32_e32 v110, v112, v112
	v_add_f32_e32 v110, v111, v110
	s_lshl_b64 s[10:11], s[6:7], 11
	s_add_u32 s10, s17, s10
	v_add_f32_dpp v110, v110, v110 quad_perm:[1,0,3,2] row_mask:0xf bank_mask:0xf bound_ctrl:1
	s_addc_u32 s11, s18, s11
	s_add_u32 s10, s10, s4
	v_add_f32_dpp v110, v110, v110 quad_perm:[2,3,0,1] row_mask:0xf bank_mask:0xf bound_ctrl:1
	s_addc_u32 s11, s11, s5
	v_cvt_pk_bf16_f32 v115, v112, v113
	v_add_f32_dpp v110, v110, v110 row_half_mirror row_mask:0xf bank_mask:0xf bound_ctrl:1
	v_lshl_add_u64 v[116:117], v[130:131], 1, s[10:11]
	global_store_dwordx2 v[116:117], v[114:115], off sc1
	v_add_f32_dpp v110, v110, v110 row_mirror row_mask:0xf bank_mask:0xf bound_ctrl:1
	v_mov_b32_e32 v111, v110
	s_nop 1
	v_permlane16_swap_b32_e32 v110, v111
	v_add_f32_e32 v110, v110, v111
	v_mov_b32_e32 v111, v110
	s_nop 1
	v_permlane32_swap_b32_e32 v110, v111
	s_and_saveexec_b64 s[10:11], vcc
	s_cbranch_execz .LBB0_776
	s_lshl_b64 s[6:7], s[6:7], 4
	s_add_u32 s28, s15, s6
	s_addc_u32 s29, s16, s7
	s_lshl_b64 s[6:7], s[8:9], 2
	s_add_u32 s6, s28, s6
	s_addc_u32 s7, s29, s7
	v_mov_b32_e32 v112, 0
	v_add_f32_e32 v110, v110, v111
	global_store_dword v112, v110, s[6:7]
.LBB0_776:
	s_or_b64 exec, exec, s[10:11]
	ds_read_b128 v[110:113], v128 offset:4160
	s_or_b32 s6, s30, 5
	s_and_b32 s28, s6, 13
	s_or_b32 s6, s31, s28
	s_ashr_i32 s7, s6, 31
	s_waitcnt vmcnt(7) lgkmcnt(0)
	v_pk_add_f32 v[106:107], v[106:107], v[110:111]
	v_pk_add_f32 v[108:109], v[108:109], v[112:113]
	v_cvt_pk_bf16_f32 v110, v106, v107
	v_mul_f32_e32 v107, v107, v107
	v_fmac_f32_e32 v107, v106, v106
	v_mul_f32_e32 v106, v109, v109
	v_fmac_f32_e32 v106, v108, v108
	v_add_f32_e32 v106, v107, v106
	s_lshl_b64 s[10:11], s[6:7], 11
	s_add_u32 s10, s17, s10
	v_add_f32_dpp v106, v106, v106 quad_perm:[1,0,3,2] row_mask:0xf bank_mask:0xf bound_ctrl:1
	s_addc_u32 s11, s18, s11
	s_add_u32 s10, s10, s4
	v_add_f32_dpp v106, v106, v106 quad_perm:[2,3,0,1] row_mask:0xf bank_mask:0xf bound_ctrl:1
	s_addc_u32 s11, s11, s5
	v_cvt_pk_bf16_f32 v111, v108, v109
	v_add_f32_dpp v106, v106, v106 row_half_mirror row_mask:0xf bank_mask:0xf bound_ctrl:1
	v_lshl_add_u64 v[112:113], v[130:131], 1, s[10:11]
	global_store_dwordx2 v[112:113], v[110:111], off sc1
	v_add_f32_dpp v106, v106, v106 row_mirror row_mask:0xf bank_mask:0xf bound_ctrl:1
	v_mov_b32_e32 v107, v106
	s_nop 1
	v_permlane16_swap_b32_e32 v106, v107
	v_add_f32_e32 v106, v106, v107
	v_mov_b32_e32 v107, v106
	s_nop 1
	v_permlane32_swap_b32_e32 v106, v107
	s_and_saveexec_b64 s[10:11], vcc
	s_cbranch_execz .LBB0_778
	s_lshl_b64 s[6:7], s[6:7], 4
	s_add_u32 s29, s15, s6
	s_addc_u32 s33, s16, s7
	s_lshl_b64 s[6:7], s[8:9], 2
	s_add_u32 s6, s29, s6
	s_addc_u32 s7, s33, s7
	v_mov_b32_e32 v108, 0
	v_add_f32_e32 v106, v106, v107
	global_store_dword v108, v106, s[6:7]
.LBB0_778:
	s_or_b64 exec, exec, s[10:11]
	ds_read_b128 v[106:109], v128 offset:5200
	s_or_b32 s6, s30, 6
	s_and_b32 s29, s6, 14
	s_or_b32 s6, s31, s29
	s_ashr_i32 s7, s6, 31
	s_waitcnt vmcnt(7) lgkmcnt(0)
	v_pk_add_f32 v[102:103], v[102:103], v[106:107]
	v_pk_add_f32 v[104:105], v[104:105], v[108:109]
	v_cvt_pk_bf16_f32 v106, v102, v103
	v_mul_f32_e32 v103, v103, v103
	v_fmac_f32_e32 v103, v102, v102
	v_mul_f32_e32 v102, v105, v105
	v_fmac_f32_e32 v102, v104, v104
	v_add_f32_e32 v102, v103, v102
	s_lshl_b64 s[10:11], s[6:7], 11
	s_add_u32 s10, s17, s10
	v_add_f32_dpp v102, v102, v102 quad_perm:[1,0,3,2] row_mask:0xf bank_mask:0xf bound_ctrl:1
	s_addc_u32 s11, s18, s11
	s_add_u32 s10, s10, s4
	v_add_f32_dpp v102, v102, v102 quad_perm:[2,3,0,1] row_mask:0xf bank_mask:0xf bound_ctrl:1
	s_addc_u32 s11, s11, s5
	v_cvt_pk_bf16_f32 v107, v104, v105
	v_add_f32_dpp v102, v102, v102 row_half_mirror row_mask:0xf bank_mask:0xf bound_ctrl:1
	v_lshl_add_u64 v[108:109], v[130:131], 1, s[10:11]
	global_store_dwordx2 v[108:109], v[106:107], off sc1
	v_add_f32_dpp v102, v102, v102 row_mirror row_mask:0xf bank_mask:0xf bound_ctrl:1
	v_mov_b32_e32 v103, v102
	s_nop 1
	v_permlane16_swap_b32_e32 v102, v103
	v_add_f32_e32 v102, v102, v103
	v_mov_b32_e32 v103, v102
	s_nop 1
	v_permlane32_swap_b32_e32 v102, v103
	s_and_saveexec_b64 s[10:11], vcc
	s_cbranch_execz .LBB0_780
	s_lshl_b64 s[6:7], s[6:7], 4
	s_add_u32 s33, s15, s6
	s_addc_u32 s34, s16, s7
	s_lshl_b64 s[6:7], s[8:9], 2
	s_add_u32 s6, s33, s6
	s_addc_u32 s7, s34, s7
	v_mov_b32_e32 v104, 0
	v_add_f32_e32 v102, v102, v103
	global_store_dword v104, v102, s[6:7]
.LBB0_780:
	s_or_b64 exec, exec, s[10:11]
	ds_read_b128 v[102:105], v128 offset:6240
	s_or_b32 s6, s30, 7
	s_and_b32 s30, s6, 15
	s_or_b32 s6, s31, s30
	s_ashr_i32 s7, s6, 31
	s_waitcnt vmcnt(7) lgkmcnt(0)
	v_pk_add_f32 v[98:99], v[98:99], v[102:103]
	v_pk_add_f32 v[100:101], v[100:101], v[104:105]
	v_cvt_pk_bf16_f32 v102, v98, v99
	v_mul_f32_e32 v99, v99, v99
	v_fmac_f32_e32 v99, v98, v98
	v_mul_f32_e32 v98, v101, v101
	v_fmac_f32_e32 v98, v100, v100
	v_add_f32_e32 v98, v99, v98
	s_lshl_b64 s[10:11], s[6:7], 11
	s_add_u32 s10, s17, s10
	v_add_f32_dpp v98, v98, v98 quad_perm:[1,0,3,2] row_mask:0xf bank_mask:0xf bound_ctrl:1
	s_addc_u32 s11, s18, s11
	s_add_u32 s10, s10, s4
	v_add_f32_dpp v98, v98, v98 quad_perm:[2,3,0,1] row_mask:0xf bank_mask:0xf bound_ctrl:1
	s_addc_u32 s11, s11, s5
	v_cvt_pk_bf16_f32 v103, v100, v101
	v_add_f32_dpp v98, v98, v98 row_half_mirror row_mask:0xf bank_mask:0xf bound_ctrl:1
	v_lshl_add_u64 v[104:105], v[130:131], 1, s[10:11]
	global_store_dwordx2 v[104:105], v[102:103], off sc1
	v_add_f32_dpp v98, v98, v98 row_mirror row_mask:0xf bank_mask:0xf bound_ctrl:1
	v_mov_b32_e32 v99, v98
	s_nop 1
	v_permlane16_swap_b32_e32 v98, v99
	v_add_f32_e32 v98, v98, v99
	v_mov_b32_e32 v99, v98
	s_nop 1
	v_permlane32_swap_b32_e32 v98, v99
	s_and_saveexec_b64 s[10:11], vcc
	s_cbranch_execz .LBB0_782
	s_lshl_b64 s[6:7], s[6:7], 4
	s_add_u32 s33, s15, s6
	s_addc_u32 s34, s16, s7
	s_lshl_b64 s[6:7], s[8:9], 2
	s_add_u32 s6, s33, s6
	s_addc_u32 s7, s34, s7
	v_mov_b32_e32 v100, 0
	v_add_f32_e32 v98, v98, v99
	global_store_dword v100, v98, s[6:7]
.LBB0_782:
	s_or_b64 exec, exec, s[10:11]
	s_or_b32 s33, s31, 32
	s_or_b32 s6, s33, s19
	s_ashr_i32 s7, s6, 31
	s_lshl_b64 s[10:11], s[6:7], 12
	s_barrier
	ds_write_b128 v132, v[94:97]
	ds_write_b128 v132, v[90:93] offset:16
	ds_write_b128 v132, v[78:81] offset:512
	ds_write_b128 v132, v[74:77] offset:528
	ds_write_b128 v132, v[86:89] offset:16640
	ds_write_b128 v132, v[82:85] offset:16656
	ds_write_b128 v132, v[70:73] offset:17152
	ds_write_b128 v132, v[66:69] offset:17168
	v_lshl_add_u64 v[66:67], v[126:127], 0, s[10:11]
	s_or_b32 s10, s33, s12
	s_ashr_i32 s11, s10, 31
	s_lshl_b64 s[10:11], s[10:11], 12
	v_lshl_add_u64 v[68:69], v[126:127], 0, s[10:11]
	s_or_b32 s10, s33, s13
	s_ashr_i32 s11, s10, 31
	s_lshl_b64 s[10:11], s[10:11], 12
	s_waitcnt lgkmcnt(0)
	s_barrier
	global_load_dwordx4 v[94:97], v[66:67], off
	global_load_dwordx4 v[90:93], v[68:69], off
	v_lshl_add_u64 v[66:67], v[126:127], 0, s[10:11]
	s_or_b32 s10, s33, s14
	s_ashr_i32 s11, s10, 31
	s_lshl_b64 s[10:11], s[10:11], 12
	v_lshl_add_u64 v[68:69], v[126:127], 0, s[10:11]
	s_or_b32 s10, s33, s20
	s_ashr_i32 s11, s10, 31
	s_lshl_b64 s[10:11], s[10:11], 12
	global_load_dwordx4 v[86:89], v[66:67], off
	global_load_dwordx4 v[82:85], v[68:69], off
	v_lshl_add_u64 v[66:67], v[126:127], 0, s[10:11]
	s_or_b32 s10, s33, s22
	s_ashr_i32 s11, s10, 31
	s_lshl_b64 s[10:11], s[10:11], 12
	v_lshl_add_u64 v[68:69], v[126:127], 0, s[10:11]
	s_or_b32 s10, s33, s21
	s_ashr_i32 s11, s10, 31
	s_lshl_b64 s[10:11], s[10:11], 12
	global_load_dwordx4 v[78:81], v[66:67], off
	global_load_dwordx4 v[74:77], v[68:69], off
	v_lshl_add_u64 v[66:67], v[126:127], 0, s[10:11]
	s_or_b32 s10, s33, s23
	s_ashr_i32 s11, s10, 31
	s_lshl_b64 s[10:11], s[10:11], 12
	v_lshl_add_u64 v[68:69], v[126:127], 0, s[10:11]
	global_load_dwordx4 v[70:73], v[66:67], off
	s_nop 0
	global_load_dwordx4 v[66:69], v[68:69], off
	ds_read_b128 v[98:101], v129
	s_lshl_b64 s[10:11], s[6:7], 11
	s_add_u32 s10, s17, s10
	s_addc_u32 s11, s18, s11
	s_add_u32 s10, s10, s4
	s_addc_u32 s11, s11, s5
	v_lshl_add_u64 v[102:103], v[130:131], 1, s[10:11]
	s_waitcnt vmcnt(7) lgkmcnt(0)
	v_pk_add_f32 v[96:97], v[96:97], v[100:101]
	v_pk_add_f32 v[94:95], v[94:95], v[98:99]
	v_cvt_pk_bf16_f32 v99, v96, v97
	v_cvt_pk_bf16_f32 v98, v94, v95
	v_mul_f32_e32 v95, v95, v95
	v_mul_f32_e32 v97, v97, v97
	v_fmac_f32_e32 v95, v94, v94
	v_fmac_f32_e32 v97, v96, v96
	v_add_f32_e32 v94, v95, v97
	global_store_dwordx2 v[102:103], v[98:99], off sc1
	s_nop 0
	v_add_f32_dpp v94, v94, v94 quad_perm:[1,0,3,2] row_mask:0xf bank_mask:0xf bound_ctrl:1
	s_nop 1
	v_add_f32_dpp v94, v94, v94 quad_perm:[2,3,0,1] row_mask:0xf bank_mask:0xf bound_ctrl:1
	s_nop 1
	v_add_f32_dpp v94, v94, v94 row_half_mirror row_mask:0xf bank_mask:0xf bound_ctrl:1
	s_nop 1
	v_add_f32_dpp v94, v94, v94 row_mirror row_mask:0xf bank_mask:0xf bound_ctrl:1
	v_mov_b32_e32 v95, v94
	s_nop 1
	v_permlane16_swap_b32_e32 v94, v95
	v_add_f32_e32 v94, v94, v95
	v_mov_b32_e32 v95, v94
	s_nop 1
	v_permlane32_swap_b32_e32 v94, v95
	s_and_saveexec_b64 s[10:11], vcc
	s_cbranch_execz .LBB0_784
	s_lshl_b64 s[6:7], s[6:7], 4
	s_add_u32 s34, s15, s6
	s_addc_u32 s35, s16, s7
	s_lshl_b64 s[6:7], s[8:9], 2
	s_add_u32 s6, s34, s6
	s_addc_u32 s7, s35, s7
	v_mov_b32_e32 v96, 0
	v_add_f32_e32 v94, v94, v95
	global_store_dword v96, v94, s[6:7]
.LBB0_784:
	s_or_b64 exec, exec, s[10:11]
	ds_read_b128 v[94:97], v128
	s_or_b32 s6, s33, s24
	s_ashr_i32 s7, s6, 31
	s_lshl_b64 s[10:11], s[6:7], 11
	s_add_u32 s10, s17, s10
	s_waitcnt vmcnt(7) lgkmcnt(0)
	v_pk_add_f32 v[90:91], v[90:91], v[94:95]
	v_pk_add_f32 v[92:93], v[92:93], v[96:97]
	v_cvt_pk_bf16_f32 v94, v90, v91
	v_mul_f32_e32 v91, v91, v91
	v_fmac_f32_e32 v91, v90, v90
	v_mul_f32_e32 v90, v93, v93
	v_fmac_f32_e32 v90, v92, v92
	v_add_f32_e32 v90, v91, v90
	s_addc_u32 s11, s18, s11
	s_add_u32 s10, s10, s4
	v_add_f32_dpp v90, v90, v90 quad_perm:[1,0,3,2] row_mask:0xf bank_mask:0xf bound_ctrl:1
	s_addc_u32 s11, s11, s5
	v_cvt_pk_bf16_f32 v95, v92, v93
	v_add_f32_dpp v90, v90, v90 quad_perm:[2,3,0,1] row_mask:0xf bank_mask:0xf bound_ctrl:1
	v_lshl_add_u64 v[96:97], v[130:131], 1, s[10:11]
	global_store_dwordx2 v[96:97], v[94:95], off sc1
	v_add_f32_dpp v90, v90, v90 row_half_mirror row_mask:0xf bank_mask:0xf bound_ctrl:1
	s_nop 1
	v_add_f32_dpp v90, v90, v90 row_mirror row_mask:0xf bank_mask:0xf bound_ctrl:1
	v_mov_b32_e32 v91, v90
	s_nop 1
	v_permlane16_swap_b32_e32 v90, v91
	v_add_f32_e32 v90, v90, v91
	v_mov_b32_e32 v91, v90
	s_nop 1
	v_permlane32_swap_b32_e32 v90, v91
	s_and_saveexec_b64 s[10:11], vcc
	s_cbranch_execz .LBB0_786
	s_lshl_b64 s[6:7], s[6:7], 4
	s_add_u32 s34, s15, s6
	s_addc_u32 s35, s16, s7
	s_lshl_b64 s[6:7], s[8:9], 2
	s_add_u32 s6, s34, s6
	s_addc_u32 s7, s35, s7
	v_mov_b32_e32 v92, 0
	v_add_f32_e32 v90, v90, v91
	global_store_dword v92, v90, s[6:7]
.LBB0_786:
	s_or_b64 exec, exec, s[10:11]
	ds_read_b128 v[90:93], v128 offset:1040
	s_or_b32 s6, s33, s25
	s_ashr_i32 s7, s6, 31
	s_lshl_b64 s[10:11], s[6:7], 11
	s_add_u32 s10, s17, s10
	s_waitcnt vmcnt(7) lgkmcnt(0)
	v_pk_add_f32 v[86:87], v[86:87], v[90:91]
	v_pk_add_f32 v[88:89], v[88:89], v[92:93]
	v_cvt_pk_bf16_f32 v90, v86, v87
	v_mul_f32_e32 v87, v87, v87
	v_fmac_f32_e32 v87, v86, v86
	v_mul_f32_e32 v86, v89, v89
	v_fmac_f32_e32 v86, v88, v88
	v_add_f32_e32 v86, v87, v86
	s_addc_u32 s11, s18, s11
	s_add_u32 s10, s10, s4
	v_add_f32_dpp v86, v86, v86 quad_perm:[1,0,3,2] row_mask:0xf bank_mask:0xf bound_ctrl:1
	s_addc_u32 s11, s11, s5
	v_cvt_pk_bf16_f32 v91, v88, v89
	v_add_f32_dpp v86, v86, v86 quad_perm:[2,3,0,1] row_mask:0xf bank_mask:0xf bound_ctrl:1
	v_lshl_add_u64 v[92:93], v[130:131], 1, s[10:11]
	global_store_dwordx2 v[92:93], v[90:91], off sc1
	v_add_f32_dpp v86, v86, v86 row_half_mirror row_mask:0xf bank_mask:0xf bound_ctrl:1
	s_nop 1
	v_add_f32_dpp v86, v86, v86 row_mirror row_mask:0xf bank_mask:0xf bound_ctrl:1
	v_mov_b32_e32 v87, v86
	s_nop 1
	v_permlane16_swap_b32_e32 v86, v87
	v_add_f32_e32 v86, v86, v87
	v_mov_b32_e32 v87, v86
	s_nop 1
	v_permlane32_swap_b32_e32 v86, v87
	s_and_saveexec_b64 s[10:11], vcc
	s_cbranch_execz .LBB0_788
	s_lshl_b64 s[6:7], s[6:7], 4
	s_add_u32 s34, s15, s6
	s_addc_u32 s35, s16, s7
	s_lshl_b64 s[6:7], s[8:9], 2
	s_add_u32 s6, s34, s6
	s_addc_u32 s7, s35, s7
	v_mov_b32_e32 v88, 0
	v_add_f32_e32 v86, v86, v87
	global_store_dword v88, v86, s[6:7]
.LBB0_788:
	s_or_b64 exec, exec, s[10:11]
	ds_read_b128 v[86:89], v128 offset:2080
	s_or_b32 s6, s33, s26
	s_ashr_i32 s7, s6, 31
	s_lshl_b64 s[10:11], s[6:7], 11
	s_add_u32 s10, s17, s10
	s_waitcnt vmcnt(7) lgkmcnt(0)
	v_pk_add_f32 v[82:83], v[82:83], v[86:87]
	v_pk_add_f32 v[84:85], v[84:85], v[88:89]
	v_cvt_pk_bf16_f32 v86, v82, v83
	v_mul_f32_e32 v83, v83, v83
	v_fmac_f32_e32 v83, v82, v82
	v_mul_f32_e32 v82, v85, v85
	v_fmac_f32_e32 v82, v84, v84
	v_add_f32_e32 v82, v83, v82
	s_addc_u32 s11, s18, s11
	s_add_u32 s10, s10, s4
	v_add_f32_dpp v82, v82, v82 quad_perm:[1,0,3,2] row_mask:0xf bank_mask:0xf bound_ctrl:1
	s_addc_u32 s11, s11, s5
	v_cvt_pk_bf16_f32 v87, v84, v85
	v_add_f32_dpp v82, v82, v82 quad_perm:[2,3,0,1] row_mask:0xf bank_mask:0xf bound_ctrl:1
	v_lshl_add_u64 v[88:89], v[130:131], 1, s[10:11]
	global_store_dwordx2 v[88:89], v[86:87], off sc1
	v_add_f32_dpp v82, v82, v82 row_half_mirror row_mask:0xf bank_mask:0xf bound_ctrl:1
	s_nop 1
	v_add_f32_dpp v82, v82, v82 row_mirror row_mask:0xf bank_mask:0xf bound_ctrl:1
	v_mov_b32_e32 v83, v82
	s_nop 1
	v_permlane16_swap_b32_e32 v82, v83
	v_add_f32_e32 v82, v82, v83
	v_mov_b32_e32 v83, v82
	s_nop 1
	v_permlane32_swap_b32_e32 v82, v83
	s_and_saveexec_b64 s[10:11], vcc
	s_cbranch_execz .LBB0_790
	s_lshl_b64 s[6:7], s[6:7], 4
	s_add_u32 s34, s15, s6
	s_addc_u32 s35, s16, s7
	s_lshl_b64 s[6:7], s[8:9], 2
	s_add_u32 s6, s34, s6
	s_addc_u32 s7, s35, s7
	v_mov_b32_e32 v84, 0
	v_add_f32_e32 v82, v82, v83
	global_store_dword v84, v82, s[6:7]
.LBB0_790:
	s_or_b64 exec, exec, s[10:11]
	ds_read_b128 v[82:85], v128 offset:3120
	s_or_b32 s6, s33, s27
	s_ashr_i32 s7, s6, 31
	s_lshl_b64 s[10:11], s[6:7], 11
	s_add_u32 s10, s17, s10
	s_waitcnt vmcnt(7) lgkmcnt(0)
	v_pk_add_f32 v[78:79], v[78:79], v[82:83]
	v_pk_add_f32 v[80:81], v[80:81], v[84:85]
	v_cvt_pk_bf16_f32 v82, v78, v79
	v_mul_f32_e32 v79, v79, v79
	v_fmac_f32_e32 v79, v78, v78
	v_mul_f32_e32 v78, v81, v81
	v_fmac_f32_e32 v78, v80, v80
	v_add_f32_e32 v78, v79, v78
	s_addc_u32 s11, s18, s11
	s_add_u32 s10, s10, s4
	v_add_f32_dpp v78, v78, v78 quad_perm:[1,0,3,2] row_mask:0xf bank_mask:0xf bound_ctrl:1
	s_addc_u32 s11, s11, s5
	v_cvt_pk_bf16_f32 v83, v80, v81
	v_add_f32_dpp v78, v78, v78 quad_perm:[2,3,0,1] row_mask:0xf bank_mask:0xf bound_ctrl:1
	v_lshl_add_u64 v[84:85], v[130:131], 1, s[10:11]
	global_store_dwordx2 v[84:85], v[82:83], off sc1
	v_add_f32_dpp v78, v78, v78 row_half_mirror row_mask:0xf bank_mask:0xf bound_ctrl:1
	s_nop 1
	v_add_f32_dpp v78, v78, v78 row_mirror row_mask:0xf bank_mask:0xf bound_ctrl:1
	v_mov_b32_e32 v79, v78
	s_nop 1
	v_permlane16_swap_b32_e32 v78, v79
	v_add_f32_e32 v78, v78, v79
	v_mov_b32_e32 v79, v78
	s_nop 1
	v_permlane32_swap_b32_e32 v78, v79
	s_and_saveexec_b64 s[10:11], vcc
	s_cbranch_execz .LBB0_792
	s_lshl_b64 s[6:7], s[6:7], 4
	s_add_u32 s34, s15, s6
	s_addc_u32 s35, s16, s7
	s_lshl_b64 s[6:7], s[8:9], 2
	s_add_u32 s6, s34, s6
	s_addc_u32 s7, s35, s7
	v_mov_b32_e32 v80, 0
	v_add_f32_e32 v78, v78, v79
	global_store_dword v80, v78, s[6:7]
.LBB0_792:
	s_or_b64 exec, exec, s[10:11]
	ds_read_b128 v[78:81], v128 offset:4160
	s_or_b32 s6, s33, s28
	s_ashr_i32 s7, s6, 31
	s_lshl_b64 s[10:11], s[6:7], 11
	s_add_u32 s10, s17, s10
	s_waitcnt vmcnt(7) lgkmcnt(0)
	v_pk_add_f32 v[74:75], v[74:75], v[78:79]
	v_pk_add_f32 v[76:77], v[76:77], v[80:81]
	v_cvt_pk_bf16_f32 v78, v74, v75
	v_mul_f32_e32 v75, v75, v75
	v_fmac_f32_e32 v75, v74, v74
	v_mul_f32_e32 v74, v77, v77
	v_fmac_f32_e32 v74, v76, v76
	v_add_f32_e32 v74, v75, v74
	s_addc_u32 s11, s18, s11
	s_add_u32 s10, s10, s4
	v_add_f32_dpp v74, v74, v74 quad_perm:[1,0,3,2] row_mask:0xf bank_mask:0xf bound_ctrl:1
	s_addc_u32 s11, s11, s5
	v_cvt_pk_bf16_f32 v79, v76, v77
	v_add_f32_dpp v74, v74, v74 quad_perm:[2,3,0,1] row_mask:0xf bank_mask:0xf bound_ctrl:1
	v_lshl_add_u64 v[80:81], v[130:131], 1, s[10:11]
	global_store_dwordx2 v[80:81], v[78:79], off sc1
	v_add_f32_dpp v74, v74, v74 row_half_mirror row_mask:0xf bank_mask:0xf bound_ctrl:1
	s_nop 1
	v_add_f32_dpp v74, v74, v74 row_mirror row_mask:0xf bank_mask:0xf bound_ctrl:1
	v_mov_b32_e32 v75, v74
	s_nop 1
	v_permlane16_swap_b32_e32 v74, v75
	v_add_f32_e32 v74, v74, v75
	v_mov_b32_e32 v75, v74
	s_nop 1
	v_permlane32_swap_b32_e32 v74, v75
	s_and_saveexec_b64 s[10:11], vcc
	s_cbranch_execz .LBB0_794
	s_lshl_b64 s[6:7], s[6:7], 4
	s_add_u32 s34, s15, s6
	s_addc_u32 s35, s16, s7
	s_lshl_b64 s[6:7], s[8:9], 2
	s_add_u32 s6, s34, s6
	s_addc_u32 s7, s35, s7
	v_mov_b32_e32 v76, 0
	v_add_f32_e32 v74, v74, v75
	global_store_dword v76, v74, s[6:7]
.LBB0_794:
	s_or_b64 exec, exec, s[10:11]
	ds_read_b128 v[74:77], v128 offset:5200
	s_or_b32 s6, s33, s29
	s_ashr_i32 s7, s6, 31
	s_lshl_b64 s[10:11], s[6:7], 11
	s_add_u32 s10, s17, s10
	s_waitcnt vmcnt(7) lgkmcnt(0)
	v_pk_add_f32 v[70:71], v[70:71], v[74:75]
	v_pk_add_f32 v[72:73], v[72:73], v[76:77]
	v_cvt_pk_bf16_f32 v74, v70, v71
	v_mul_f32_e32 v71, v71, v71
	v_fmac_f32_e32 v71, v70, v70
	v_mul_f32_e32 v70, v73, v73
	v_fmac_f32_e32 v70, v72, v72
	v_add_f32_e32 v70, v71, v70
	s_addc_u32 s11, s18, s11
	s_add_u32 s10, s10, s4
	v_add_f32_dpp v70, v70, v70 quad_perm:[1,0,3,2] row_mask:0xf bank_mask:0xf bound_ctrl:1
	s_addc_u32 s11, s11, s5
	v_cvt_pk_bf16_f32 v75, v72, v73
	v_add_f32_dpp v70, v70, v70 quad_perm:[2,3,0,1] row_mask:0xf bank_mask:0xf bound_ctrl:1
	v_lshl_add_u64 v[76:77], v[130:131], 1, s[10:11]
	global_store_dwordx2 v[76:77], v[74:75], off sc1
	v_add_f32_dpp v70, v70, v70 row_half_mirror row_mask:0xf bank_mask:0xf bound_ctrl:1
	s_nop 1
	v_add_f32_dpp v70, v70, v70 row_mirror row_mask:0xf bank_mask:0xf bound_ctrl:1
	v_mov_b32_e32 v71, v70
	s_nop 1
	v_permlane16_swap_b32_e32 v70, v71
	v_add_f32_e32 v70, v70, v71
	v_mov_b32_e32 v71, v70
	s_nop 1
	v_permlane32_swap_b32_e32 v70, v71
	s_and_saveexec_b64 s[10:11], vcc
	s_cbranch_execz .LBB0_796
	s_lshl_b64 s[6:7], s[6:7], 4
	s_add_u32 s34, s15, s6
	s_addc_u32 s35, s16, s7
	s_lshl_b64 s[6:7], s[8:9], 2
	s_add_u32 s6, s34, s6
	s_addc_u32 s7, s35, s7
	v_mov_b32_e32 v72, 0
	v_add_f32_e32 v70, v70, v71
	global_store_dword v72, v70, s[6:7]
.LBB0_796:
	s_or_b64 exec, exec, s[10:11]
	ds_read_b128 v[70:73], v128 offset:6240
	s_or_b32 s6, s33, s30
	s_ashr_i32 s7, s6, 31
	s_lshl_b64 s[10:11], s[6:7], 11
	s_add_u32 s10, s17, s10
	s_waitcnt vmcnt(7) lgkmcnt(0)
	v_pk_add_f32 v[66:67], v[66:67], v[70:71]
	v_pk_add_f32 v[68:69], v[68:69], v[72:73]
	v_cvt_pk_bf16_f32 v70, v66, v67
	v_mul_f32_e32 v67, v67, v67
	v_fmac_f32_e32 v67, v66, v66
	v_mul_f32_e32 v66, v69, v69
	v_fmac_f32_e32 v66, v68, v68
	v_add_f32_e32 v66, v67, v66
	s_addc_u32 s11, s18, s11
	s_add_u32 s10, s10, s4
	v_add_f32_dpp v66, v66, v66 quad_perm:[1,0,3,2] row_mask:0xf bank_mask:0xf bound_ctrl:1
	s_addc_u32 s11, s11, s5
	v_cvt_pk_bf16_f32 v71, v68, v69
	v_add_f32_dpp v66, v66, v66 quad_perm:[2,3,0,1] row_mask:0xf bank_mask:0xf bound_ctrl:1
	v_lshl_add_u64 v[72:73], v[130:131], 1, s[10:11]
	global_store_dwordx2 v[72:73], v[70:71], off sc1
	v_add_f32_dpp v66, v66, v66 row_half_mirror row_mask:0xf bank_mask:0xf bound_ctrl:1
	s_nop 1
	v_add_f32_dpp v66, v66, v66 row_mirror row_mask:0xf bank_mask:0xf bound_ctrl:1
	v_mov_b32_e32 v67, v66
	s_nop 1
	v_permlane16_swap_b32_e32 v66, v67
	v_add_f32_e32 v66, v66, v67
	v_mov_b32_e32 v67, v66
	s_nop 1
	v_permlane32_swap_b32_e32 v66, v67
	s_and_saveexec_b64 s[10:11], vcc
	s_cbranch_execz .LBB0_798
	s_lshl_b64 s[6:7], s[6:7], 4
	s_add_u32 s33, s15, s6
	s_addc_u32 s34, s16, s7
	s_lshl_b64 s[6:7], s[8:9], 2
	s_add_u32 s6, s33, s6
	s_addc_u32 s7, s34, s7
	v_mov_b32_e32 v68, 0
	v_add_f32_e32 v66, v66, v67
	global_store_dword v68, v66, s[6:7]
.LBB0_798:
	s_or_b64 exec, exec, s[10:11]
	s_addk_i32 s31, 0x80
	s_or_b32 s6, s31, s19
	s_ashr_i32 s7, s6, 31
	s_lshl_b64 s[10:11], s[6:7], 12
	s_barrier
	ds_write_b128 v132, v[62:65]
	ds_write_b128 v132, v[58:61] offset:16
	ds_write_b128 v132, v[46:49] offset:512
	ds_write_b128 v132, v[42:45] offset:528
	ds_write_b128 v132, v[54:57] offset:16640
	ds_write_b128 v132, v[50:53] offset:16656
	ds_write_b128 v132, v[38:41] offset:17152
	ds_write_b128 v132, v[34:37] offset:17168
	v_lshl_add_u64 v[34:35], v[126:127], 0, s[10:11]
	s_or_b32 s10, s31, s12
	s_ashr_i32 s11, s10, 31
	s_lshl_b64 s[10:11], s[10:11], 12
	v_lshl_add_u64 v[36:37], v[126:127], 0, s[10:11]
	s_or_b32 s10, s31, s13
	s_ashr_i32 s11, s10, 31
	s_lshl_b64 s[10:11], s[10:11], 12
	s_waitcnt lgkmcnt(0)
	s_barrier
	global_load_dwordx4 v[62:65], v[34:35], off
	global_load_dwordx4 v[58:61], v[36:37], off
	v_lshl_add_u64 v[34:35], v[126:127], 0, s[10:11]
	s_or_b32 s10, s31, s14
	s_ashr_i32 s11, s10, 31
	s_lshl_b64 s[10:11], s[10:11], 12
	v_lshl_add_u64 v[36:37], v[126:127], 0, s[10:11]
	s_or_b32 s10, s31, s20
	s_ashr_i32 s11, s10, 31
	s_lshl_b64 s[10:11], s[10:11], 12
	global_load_dwordx4 v[54:57], v[34:35], off
	global_load_dwordx4 v[50:53], v[36:37], off
	v_lshl_add_u64 v[34:35], v[126:127], 0, s[10:11]
	s_or_b32 s10, s31, s22
	s_ashr_i32 s11, s10, 31
	s_lshl_b64 s[10:11], s[10:11], 12
	v_lshl_add_u64 v[36:37], v[126:127], 0, s[10:11]
	s_or_b32 s10, s31, s21
	s_ashr_i32 s11, s10, 31
	s_lshl_b64 s[10:11], s[10:11], 12
	global_load_dwordx4 v[46:49], v[34:35], off
	global_load_dwordx4 v[42:45], v[36:37], off
	v_lshl_add_u64 v[34:35], v[126:127], 0, s[10:11]
	s_or_b32 s10, s31, s23
	s_ashr_i32 s11, s10, 31
	s_lshl_b64 s[10:11], s[10:11], 12
	v_lshl_add_u64 v[36:37], v[126:127], 0, s[10:11]
	global_load_dwordx4 v[38:41], v[34:35], off
	s_nop 0
	global_load_dwordx4 v[34:37], v[36:37], off
	ds_read_b128 v[66:69], v129
	s_lshl_b64 s[10:11], s[6:7], 11
	s_add_u32 s10, s17, s10
	s_addc_u32 s11, s18, s11
	s_add_u32 s10, s10, s4
	s_addc_u32 s11, s11, s5
	v_lshl_add_u64 v[70:71], v[130:131], 1, s[10:11]
	s_waitcnt vmcnt(7) lgkmcnt(0)
	v_pk_add_f32 v[64:65], v[64:65], v[68:69]
	v_pk_add_f32 v[62:63], v[62:63], v[66:67]
	v_cvt_pk_bf16_f32 v67, v64, v65
	v_cvt_pk_bf16_f32 v66, v62, v63
	v_mul_f32_e32 v63, v63, v63
	v_mul_f32_e32 v65, v65, v65
	v_fmac_f32_e32 v63, v62, v62
	v_fmac_f32_e32 v65, v64, v64
	v_add_f32_e32 v62, v63, v65
	global_store_dwordx2 v[70:71], v[66:67], off sc1
	s_nop 0
	v_add_f32_dpp v62, v62, v62 quad_perm:[1,0,3,2] row_mask:0xf bank_mask:0xf bound_ctrl:1
	s_nop 1
	v_add_f32_dpp v62, v62, v62 quad_perm:[2,3,0,1] row_mask:0xf bank_mask:0xf bound_ctrl:1
	s_nop 1
	v_add_f32_dpp v62, v62, v62 row_half_mirror row_mask:0xf bank_mask:0xf bound_ctrl:1
	s_nop 1
	v_add_f32_dpp v62, v62, v62 row_mirror row_mask:0xf bank_mask:0xf bound_ctrl:1
	v_mov_b32_e32 v63, v62
	s_nop 1
	v_permlane16_swap_b32_e32 v62, v63
	v_add_f32_e32 v62, v62, v63
	v_mov_b32_e32 v63, v62
	s_nop 1
	v_permlane32_swap_b32_e32 v62, v63
	s_and_saveexec_b64 s[10:11], vcc
	s_cbranch_execz .LBB0_800
	s_lshl_b64 s[6:7], s[6:7], 4
	s_add_u32 s33, s15, s6
	s_addc_u32 s34, s16, s7
	s_lshl_b64 s[6:7], s[8:9], 2
	s_add_u32 s6, s33, s6
	s_addc_u32 s7, s34, s7
	v_mov_b32_e32 v64, 0
	v_add_f32_e32 v62, v62, v63
	global_store_dword v64, v62, s[6:7]
.LBB0_800:
	s_or_b64 exec, exec, s[10:11]
	ds_read_b128 v[62:65], v128
	s_or_b32 s6, s31, s24
	s_ashr_i32 s7, s6, 31
	s_lshl_b64 s[10:11], s[6:7], 11
	s_add_u32 s10, s17, s10
	s_waitcnt vmcnt(7) lgkmcnt(0)
	v_pk_add_f32 v[58:59], v[58:59], v[62:63]
	v_pk_add_f32 v[60:61], v[60:61], v[64:65]
	v_cvt_pk_bf16_f32 v62, v58, v59
	v_mul_f32_e32 v59, v59, v59
	v_fmac_f32_e32 v59, v58, v58
	v_mul_f32_e32 v58, v61, v61
	v_fmac_f32_e32 v58, v60, v60
	v_add_f32_e32 v58, v59, v58
	s_addc_u32 s11, s18, s11
	s_add_u32 s10, s10, s4
	v_add_f32_dpp v58, v58, v58 quad_perm:[1,0,3,2] row_mask:0xf bank_mask:0xf bound_ctrl:1
	s_addc_u32 s11, s11, s5
	v_cvt_pk_bf16_f32 v63, v60, v61
	v_add_f32_dpp v58, v58, v58 quad_perm:[2,3,0,1] row_mask:0xf bank_mask:0xf bound_ctrl:1
	v_lshl_add_u64 v[64:65], v[130:131], 1, s[10:11]
	global_store_dwordx2 v[64:65], v[62:63], off sc1
	v_add_f32_dpp v58, v58, v58 row_half_mirror row_mask:0xf bank_mask:0xf bound_ctrl:1
	s_nop 1
	v_add_f32_dpp v58, v58, v58 row_mirror row_mask:0xf bank_mask:0xf bound_ctrl:1
	v_mov_b32_e32 v59, v58
	s_nop 1
	v_permlane16_swap_b32_e32 v58, v59
	v_add_f32_e32 v58, v58, v59
	v_mov_b32_e32 v59, v58
	s_nop 1
	v_permlane32_swap_b32_e32 v58, v59
	s_and_saveexec_b64 s[10:11], vcc
	s_cbranch_execz .LBB0_802
	s_lshl_b64 s[6:7], s[6:7], 4
	s_add_u32 s33, s15, s6
	s_addc_u32 s34, s16, s7
	s_lshl_b64 s[6:7], s[8:9], 2
	s_add_u32 s6, s33, s6
	s_addc_u32 s7, s34, s7
	v_mov_b32_e32 v60, 0
	v_add_f32_e32 v58, v58, v59
	global_store_dword v60, v58, s[6:7]
.LBB0_802:
	s_or_b64 exec, exec, s[10:11]
	ds_read_b128 v[58:61], v128 offset:1040
	s_or_b32 s6, s31, s25
	s_ashr_i32 s7, s6, 31
	s_lshl_b64 s[10:11], s[6:7], 11
	s_add_u32 s10, s17, s10
	s_waitcnt vmcnt(7) lgkmcnt(0)
	v_pk_add_f32 v[54:55], v[54:55], v[58:59]
	v_pk_add_f32 v[56:57], v[56:57], v[60:61]
	v_cvt_pk_bf16_f32 v58, v54, v55
	v_mul_f32_e32 v55, v55, v55
	v_fmac_f32_e32 v55, v54, v54
	v_mul_f32_e32 v54, v57, v57
	v_fmac_f32_e32 v54, v56, v56
	v_add_f32_e32 v54, v55, v54
	s_addc_u32 s11, s18, s11
	s_add_u32 s10, s10, s4
	v_add_f32_dpp v54, v54, v54 quad_perm:[1,0,3,2] row_mask:0xf bank_mask:0xf bound_ctrl:1
	s_addc_u32 s11, s11, s5
	v_cvt_pk_bf16_f32 v59, v56, v57
	v_add_f32_dpp v54, v54, v54 quad_perm:[2,3,0,1] row_mask:0xf bank_mask:0xf bound_ctrl:1
	v_lshl_add_u64 v[60:61], v[130:131], 1, s[10:11]
	global_store_dwordx2 v[60:61], v[58:59], off sc1
	v_add_f32_dpp v54, v54, v54 row_half_mirror row_mask:0xf bank_mask:0xf bound_ctrl:1
	s_nop 1
	v_add_f32_dpp v54, v54, v54 row_mirror row_mask:0xf bank_mask:0xf bound_ctrl:1
	v_mov_b32_e32 v55, v54
	s_nop 1
	v_permlane16_swap_b32_e32 v54, v55
	v_add_f32_e32 v54, v54, v55
	v_mov_b32_e32 v55, v54
	s_nop 1
	v_permlane32_swap_b32_e32 v54, v55
	s_and_saveexec_b64 s[10:11], vcc
	s_cbranch_execz .LBB0_804
	s_lshl_b64 s[6:7], s[6:7], 4
	s_add_u32 s33, s15, s6
	s_addc_u32 s34, s16, s7
	s_lshl_b64 s[6:7], s[8:9], 2
	s_add_u32 s6, s33, s6
	s_addc_u32 s7, s34, s7
	v_mov_b32_e32 v56, 0
	v_add_f32_e32 v54, v54, v55
	global_store_dword v56, v54, s[6:7]
.LBB0_804:
	s_or_b64 exec, exec, s[10:11]
	ds_read_b128 v[54:57], v128 offset:2080
	s_or_b32 s6, s31, s26
	s_ashr_i32 s7, s6, 31
	s_lshl_b64 s[10:11], s[6:7], 11
	s_add_u32 s10, s17, s10
	s_waitcnt vmcnt(7) lgkmcnt(0)
	v_pk_add_f32 v[50:51], v[50:51], v[54:55]
	v_pk_add_f32 v[52:53], v[52:53], v[56:57]
	v_cvt_pk_bf16_f32 v54, v50, v51
	v_mul_f32_e32 v51, v51, v51
	v_fmac_f32_e32 v51, v50, v50
	v_mul_f32_e32 v50, v53, v53
	v_fmac_f32_e32 v50, v52, v52
	v_add_f32_e32 v50, v51, v50
	s_addc_u32 s11, s18, s11
	s_add_u32 s10, s10, s4
	v_add_f32_dpp v50, v50, v50 quad_perm:[1,0,3,2] row_mask:0xf bank_mask:0xf bound_ctrl:1
	s_addc_u32 s11, s11, s5
	v_cvt_pk_bf16_f32 v55, v52, v53
	v_add_f32_dpp v50, v50, v50 quad_perm:[2,3,0,1] row_mask:0xf bank_mask:0xf bound_ctrl:1
	v_lshl_add_u64 v[56:57], v[130:131], 1, s[10:11]
	global_store_dwordx2 v[56:57], v[54:55], off sc1
	v_add_f32_dpp v50, v50, v50 row_half_mirror row_mask:0xf bank_mask:0xf bound_ctrl:1
	s_nop 1
	v_add_f32_dpp v50, v50, v50 row_mirror row_mask:0xf bank_mask:0xf bound_ctrl:1
	v_mov_b32_e32 v51, v50
	s_nop 1
	v_permlane16_swap_b32_e32 v50, v51
	v_add_f32_e32 v50, v50, v51
	v_mov_b32_e32 v51, v50
	s_nop 1
	v_permlane32_swap_b32_e32 v50, v51
	s_and_saveexec_b64 s[10:11], vcc
	s_cbranch_execz .LBB0_806
	s_lshl_b64 s[6:7], s[6:7], 4
	s_add_u32 s33, s15, s6
	s_addc_u32 s34, s16, s7
	s_lshl_b64 s[6:7], s[8:9], 2
	s_add_u32 s6, s33, s6
	s_addc_u32 s7, s34, s7
	v_mov_b32_e32 v52, 0
	v_add_f32_e32 v50, v50, v51
	global_store_dword v52, v50, s[6:7]
.LBB0_806:
	s_or_b64 exec, exec, s[10:11]
	ds_read_b128 v[50:53], v128 offset:3120
	s_or_b32 s6, s31, s27
	s_ashr_i32 s7, s6, 31
	s_lshl_b64 s[10:11], s[6:7], 11
	s_add_u32 s10, s17, s10
	s_waitcnt vmcnt(7) lgkmcnt(0)
	v_pk_add_f32 v[46:47], v[46:47], v[50:51]
	v_pk_add_f32 v[48:49], v[48:49], v[52:53]
	v_cvt_pk_bf16_f32 v50, v46, v47
	v_mul_f32_e32 v47, v47, v47
	v_fmac_f32_e32 v47, v46, v46
	v_mul_f32_e32 v46, v49, v49
	v_fmac_f32_e32 v46, v48, v48
	v_add_f32_e32 v46, v47, v46
	s_addc_u32 s11, s18, s11
	s_add_u32 s10, s10, s4
	v_add_f32_dpp v46, v46, v46 quad_perm:[1,0,3,2] row_mask:0xf bank_mask:0xf bound_ctrl:1
	s_addc_u32 s11, s11, s5
	v_cvt_pk_bf16_f32 v51, v48, v49
	v_add_f32_dpp v46, v46, v46 quad_perm:[2,3,0,1] row_mask:0xf bank_mask:0xf bound_ctrl:1
	v_lshl_add_u64 v[52:53], v[130:131], 1, s[10:11]
	global_store_dwordx2 v[52:53], v[50:51], off sc1
	v_add_f32_dpp v46, v46, v46 row_half_mirror row_mask:0xf bank_mask:0xf bound_ctrl:1
	s_nop 1
	v_add_f32_dpp v46, v46, v46 row_mirror row_mask:0xf bank_mask:0xf bound_ctrl:1
	v_mov_b32_e32 v47, v46
	s_nop 1
	v_permlane16_swap_b32_e32 v46, v47
	v_add_f32_e32 v46, v46, v47
	v_mov_b32_e32 v47, v46
	s_nop 1
	v_permlane32_swap_b32_e32 v46, v47
	s_and_saveexec_b64 s[10:11], vcc
	s_cbranch_execz .LBB0_808
	s_lshl_b64 s[6:7], s[6:7], 4
	s_add_u32 s33, s15, s6
	s_addc_u32 s34, s16, s7
	s_lshl_b64 s[6:7], s[8:9], 2
	s_add_u32 s6, s33, s6
	s_addc_u32 s7, s34, s7
	v_mov_b32_e32 v48, 0
	v_add_f32_e32 v46, v46, v47
	global_store_dword v48, v46, s[6:7]
.LBB0_808:
	s_or_b64 exec, exec, s[10:11]
	ds_read_b128 v[46:49], v128 offset:4160
	s_or_b32 s6, s31, s28
	s_ashr_i32 s7, s6, 31
	s_lshl_b64 s[10:11], s[6:7], 11
	s_add_u32 s10, s17, s10
	s_waitcnt vmcnt(7) lgkmcnt(0)
	v_pk_add_f32 v[42:43], v[42:43], v[46:47]
	v_pk_add_f32 v[44:45], v[44:45], v[48:49]
	v_cvt_pk_bf16_f32 v46, v42, v43
	v_mul_f32_e32 v43, v43, v43
	v_fmac_f32_e32 v43, v42, v42
	v_mul_f32_e32 v42, v45, v45
	v_fmac_f32_e32 v42, v44, v44
	v_add_f32_e32 v42, v43, v42
	s_addc_u32 s11, s18, s11
	s_add_u32 s10, s10, s4
	v_add_f32_dpp v42, v42, v42 quad_perm:[1,0,3,2] row_mask:0xf bank_mask:0xf bound_ctrl:1
	s_addc_u32 s11, s11, s5
	v_cvt_pk_bf16_f32 v47, v44, v45
	v_add_f32_dpp v42, v42, v42 quad_perm:[2,3,0,1] row_mask:0xf bank_mask:0xf bound_ctrl:1
	v_lshl_add_u64 v[48:49], v[130:131], 1, s[10:11]
	global_store_dwordx2 v[48:49], v[46:47], off sc1
	v_add_f32_dpp v42, v42, v42 row_half_mirror row_mask:0xf bank_mask:0xf bound_ctrl:1
	s_nop 1
	v_add_f32_dpp v42, v42, v42 row_mirror row_mask:0xf bank_mask:0xf bound_ctrl:1
	v_mov_b32_e32 v43, v42
	s_nop 1
	v_permlane16_swap_b32_e32 v42, v43
	v_add_f32_e32 v42, v42, v43
	v_mov_b32_e32 v43, v42
	s_nop 1
	v_permlane32_swap_b32_e32 v42, v43
	s_and_saveexec_b64 s[10:11], vcc
	s_cbranch_execz .LBB0_810
	s_lshl_b64 s[6:7], s[6:7], 4
	s_add_u32 s33, s15, s6
	s_addc_u32 s34, s16, s7
	s_lshl_b64 s[6:7], s[8:9], 2
	s_add_u32 s6, s33, s6
	s_addc_u32 s7, s34, s7
	v_mov_b32_e32 v44, 0
	v_add_f32_e32 v42, v42, v43
	global_store_dword v44, v42, s[6:7]
.LBB0_810:
	s_or_b64 exec, exec, s[10:11]
	ds_read_b128 v[42:45], v128 offset:5200
	s_or_b32 s6, s31, s29
	s_ashr_i32 s7, s6, 31
	s_lshl_b64 s[10:11], s[6:7], 11
	s_add_u32 s10, s17, s10
	s_waitcnt vmcnt(7) lgkmcnt(0)
	v_pk_add_f32 v[38:39], v[38:39], v[42:43]
	v_pk_add_f32 v[40:41], v[40:41], v[44:45]
	v_cvt_pk_bf16_f32 v42, v38, v39
	v_mul_f32_e32 v39, v39, v39
	v_fmac_f32_e32 v39, v38, v38
	v_mul_f32_e32 v38, v41, v41
	v_fmac_f32_e32 v38, v40, v40
	v_add_f32_e32 v38, v39, v38
	s_addc_u32 s11, s18, s11
	s_add_u32 s10, s10, s4
	v_add_f32_dpp v38, v38, v38 quad_perm:[1,0,3,2] row_mask:0xf bank_mask:0xf bound_ctrl:1
	s_addc_u32 s11, s11, s5
	v_cvt_pk_bf16_f32 v43, v40, v41
	v_add_f32_dpp v38, v38, v38 quad_perm:[2,3,0,1] row_mask:0xf bank_mask:0xf bound_ctrl:1
	v_lshl_add_u64 v[44:45], v[130:131], 1, s[10:11]
	global_store_dwordx2 v[44:45], v[42:43], off sc1
	v_add_f32_dpp v38, v38, v38 row_half_mirror row_mask:0xf bank_mask:0xf bound_ctrl:1
	s_nop 1
	v_add_f32_dpp v38, v38, v38 row_mirror row_mask:0xf bank_mask:0xf bound_ctrl:1
	v_mov_b32_e32 v39, v38
	s_nop 1
	v_permlane16_swap_b32_e32 v38, v39
	v_add_f32_e32 v38, v38, v39
	v_mov_b32_e32 v39, v38
	s_nop 1
	v_permlane32_swap_b32_e32 v38, v39
	s_and_saveexec_b64 s[10:11], vcc
	s_cbranch_execz .LBB0_812
	s_lshl_b64 s[6:7], s[6:7], 4
	s_add_u32 s33, s15, s6
	s_addc_u32 s34, s16, s7
	s_lshl_b64 s[6:7], s[8:9], 2
	s_add_u32 s6, s33, s6
	s_addc_u32 s7, s34, s7
	v_mov_b32_e32 v40, 0
	v_add_f32_e32 v38, v38, v39
	global_store_dword v40, v38, s[6:7]
.LBB0_812:
	s_or_b64 exec, exec, s[10:11]
	ds_read_b128 v[38:41], v128 offset:6240
	s_or_b32 s6, s31, s30
	s_ashr_i32 s7, s6, 31
	s_lshl_b64 s[10:11], s[6:7], 11
	s_add_u32 s10, s17, s10
	s_waitcnt vmcnt(7) lgkmcnt(0)
	v_pk_add_f32 v[34:35], v[34:35], v[38:39]
	v_pk_add_f32 v[36:37], v[36:37], v[40:41]
	v_cvt_pk_bf16_f32 v38, v34, v35
	v_mul_f32_e32 v35, v35, v35
	v_fmac_f32_e32 v35, v34, v34
	v_mul_f32_e32 v34, v37, v37
	v_fmac_f32_e32 v34, v36, v36
	v_add_f32_e32 v34, v35, v34
	s_addc_u32 s11, s18, s11
	s_add_u32 s10, s10, s4
	v_add_f32_dpp v34, v34, v34 quad_perm:[1,0,3,2] row_mask:0xf bank_mask:0xf bound_ctrl:1
	s_addc_u32 s11, s11, s5
	v_cvt_pk_bf16_f32 v39, v36, v37
	v_add_f32_dpp v34, v34, v34 quad_perm:[2,3,0,1] row_mask:0xf bank_mask:0xf bound_ctrl:1
	v_lshl_add_u64 v[40:41], v[130:131], 1, s[10:11]
	global_store_dwordx2 v[40:41], v[38:39], off sc1
	v_add_f32_dpp v34, v34, v34 row_half_mirror row_mask:0xf bank_mask:0xf bound_ctrl:1
	s_nop 1
	v_add_f32_dpp v34, v34, v34 row_mirror row_mask:0xf bank_mask:0xf bound_ctrl:1
	v_mov_b32_e32 v35, v34
	s_nop 1
	v_permlane16_swap_b32_e32 v34, v35
	v_add_f32_e32 v34, v34, v35
	v_mov_b32_e32 v35, v34
	s_nop 1
	v_permlane32_swap_b32_e32 v34, v35
	s_and_saveexec_b64 s[10:11], vcc
	s_cbranch_execz .LBB0_814
	s_lshl_b64 s[6:7], s[6:7], 4
	s_add_u32 s33, s15, s6
	s_addc_u32 s34, s16, s7
	s_lshl_b64 s[6:7], s[8:9], 2
	s_add_u32 s6, s33, s6
	s_addc_u32 s7, s34, s7
	v_mov_b32_e32 v36, 0
	v_add_f32_e32 v34, v34, v35
	global_store_dword v36, v34, s[6:7]
.LBB0_814:
	s_or_b64 exec, exec, s[10:11]
	s_or_b32 s31, s31, 32
	s_or_b32 s6, s31, s19
	s_ashr_i32 s7, s6, 31
	s_lshl_b64 s[10:11], s[6:7], 12
	s_barrier
	ds_write_b128 v132, v[30:33]
	ds_write_b128 v132, v[26:29] offset:16
	ds_write_b128 v132, v[14:17] offset:512
	ds_write_b128 v132, v[10:13] offset:528
	ds_write_b128 v132, v[22:25] offset:16640
	ds_write_b128 v132, v[18:21] offset:16656
	ds_write_b128 v132, v[6:9] offset:17152
	ds_write_b128 v132, v[2:5] offset:17168
	v_lshl_add_u64 v[2:3], v[126:127], 0, s[10:11]
	s_or_b32 s10, s31, s12
	s_ashr_i32 s11, s10, 31
	s_lshl_b64 s[10:11], s[10:11], 12
	v_lshl_add_u64 v[4:5], v[126:127], 0, s[10:11]
	s_or_b32 s10, s31, s13
	s_ashr_i32 s11, s10, 31
	s_lshl_b64 s[10:11], s[10:11], 12
	s_waitcnt lgkmcnt(0)
	s_barrier
	global_load_dwordx4 v[30:33], v[2:3], off
	global_load_dwordx4 v[26:29], v[4:5], off
	v_lshl_add_u64 v[2:3], v[126:127], 0, s[10:11]
	s_or_b32 s10, s31, s14
	s_ashr_i32 s11, s10, 31
	s_lshl_b64 s[10:11], s[10:11], 12
	v_lshl_add_u64 v[4:5], v[126:127], 0, s[10:11]
	s_or_b32 s10, s31, s20
	s_ashr_i32 s11, s10, 31
	s_lshl_b64 s[10:11], s[10:11], 12
	global_load_dwordx4 v[22:25], v[2:3], off
	global_load_dwordx4 v[18:21], v[4:5], off
	v_lshl_add_u64 v[2:3], v[126:127], 0, s[10:11]
	s_or_b32 s10, s31, s22
	s_ashr_i32 s11, s10, 31
	s_lshl_b64 s[10:11], s[10:11], 12
	v_lshl_add_u64 v[4:5], v[126:127], 0, s[10:11]
	s_or_b32 s10, s31, s21
	s_ashr_i32 s11, s10, 31
	s_lshl_b64 s[10:11], s[10:11], 12
	v_lshl_add_u64 v[34:35], v[126:127], 0, s[10:11]
	s_or_b32 s10, s31, s23
	s_ashr_i32 s11, s10, 31
	s_lshl_b64 s[10:11], s[10:11], 12
	global_load_dwordx4 v[14:17], v[2:3], off
	global_load_dwordx4 v[10:13], v[4:5], off
	v_lshl_add_u64 v[36:37], v[126:127], 0, s[10:11]
	global_load_dwordx4 v[6:9], v[34:35], off
	global_load_dwordx4 v[2:5], v[36:37], off
	ds_read_b128 v[34:37], v129
	s_lshl_b64 s[10:11], s[6:7], 11
	s_add_u32 s10, s17, s10
	s_addc_u32 s11, s18, s11
	s_add_u32 s10, s10, s4
	s_addc_u32 s11, s11, s5
	v_lshl_add_u64 v[38:39], v[130:131], 1, s[10:11]
	s_waitcnt vmcnt(7) lgkmcnt(0)
	v_pk_add_f32 v[32:33], v[32:33], v[36:37]
	v_pk_add_f32 v[30:31], v[30:31], v[34:35]
	v_cvt_pk_bf16_f32 v35, v32, v33
	v_cvt_pk_bf16_f32 v34, v30, v31
	v_mul_f32_e32 v31, v31, v31
	v_mul_f32_e32 v33, v33, v33
	v_fmac_f32_e32 v31, v30, v30
	v_fmac_f32_e32 v33, v32, v32
	v_add_f32_e32 v30, v31, v33
	global_store_dwordx2 v[38:39], v[34:35], off sc1
	s_nop 0
	v_add_f32_dpp v30, v30, v30 quad_perm:[1,0,3,2] row_mask:0xf bank_mask:0xf bound_ctrl:1
	s_nop 1
	v_add_f32_dpp v30, v30, v30 quad_perm:[2,3,0,1] row_mask:0xf bank_mask:0xf bound_ctrl:1
	s_nop 1
	v_add_f32_dpp v30, v30, v30 row_half_mirror row_mask:0xf bank_mask:0xf bound_ctrl:1
	s_nop 1
	v_add_f32_dpp v30, v30, v30 row_mirror row_mask:0xf bank_mask:0xf bound_ctrl:1
	v_mov_b32_e32 v31, v30
	s_nop 1
	v_permlane16_swap_b32_e32 v30, v31
	v_add_f32_e32 v30, v30, v31
	v_mov_b32_e32 v31, v30
	s_nop 1
	v_permlane32_swap_b32_e32 v30, v31
	s_and_saveexec_b64 s[10:11], vcc
	s_cbranch_execz .LBB0_816
	s_lshl_b64 s[6:7], s[6:7], 4
	s_add_u32 s12, s15, s6
	s_addc_u32 s13, s16, s7
	s_lshl_b64 s[6:7], s[8:9], 2
	s_add_u32 s6, s12, s6
	s_addc_u32 s7, s13, s7
	v_mov_b32_e32 v32, 0
	v_add_f32_e32 v30, v30, v31
	global_store_dword v32, v30, s[6:7]
.LBB0_816:
	s_or_b64 exec, exec, s[10:11]
	ds_read_b128 v[30:33], v128
	s_or_b32 s6, s31, s24
	s_ashr_i32 s7, s6, 31
	s_lshl_b64 s[10:11], s[6:7], 11
	s_add_u32 s10, s17, s10
	s_waitcnt vmcnt(7) lgkmcnt(0)
	v_pk_add_f32 v[26:27], v[26:27], v[30:31]
	v_pk_add_f32 v[28:29], v[28:29], v[32:33]
	v_cvt_pk_bf16_f32 v30, v26, v27
	v_mul_f32_e32 v27, v27, v27
	v_fmac_f32_e32 v27, v26, v26
	v_mul_f32_e32 v26, v29, v29
	v_fmac_f32_e32 v26, v28, v28
	v_add_f32_e32 v26, v27, v26
	s_addc_u32 s11, s18, s11
	s_add_u32 s10, s10, s4
	v_add_f32_dpp v26, v26, v26 quad_perm:[1,0,3,2] row_mask:0xf bank_mask:0xf bound_ctrl:1
	s_addc_u32 s11, s11, s5
	v_cvt_pk_bf16_f32 v31, v28, v29
	v_add_f32_dpp v26, v26, v26 quad_perm:[2,3,0,1] row_mask:0xf bank_mask:0xf bound_ctrl:1
	v_lshl_add_u64 v[32:33], v[130:131], 1, s[10:11]
	global_store_dwordx2 v[32:33], v[30:31], off sc1
	v_add_f32_dpp v26, v26, v26 row_half_mirror row_mask:0xf bank_mask:0xf bound_ctrl:1
	s_nop 1
	v_add_f32_dpp v26, v26, v26 row_mirror row_mask:0xf bank_mask:0xf bound_ctrl:1
	v_mov_b32_e32 v27, v26
	s_nop 1
	v_permlane16_swap_b32_e32 v26, v27
	v_add_f32_e32 v26, v26, v27
	v_mov_b32_e32 v27, v26
	s_nop 1
	v_permlane32_swap_b32_e32 v26, v27
	s_and_saveexec_b64 s[10:11], vcc
	s_cbranch_execz .LBB0_818
	s_lshl_b64 s[6:7], s[6:7], 4
	s_add_u32 s12, s15, s6
	s_addc_u32 s13, s16, s7
	s_lshl_b64 s[6:7], s[8:9], 2
	s_add_u32 s6, s12, s6
	s_addc_u32 s7, s13, s7
	v_mov_b32_e32 v28, 0
	v_add_f32_e32 v26, v26, v27
	global_store_dword v28, v26, s[6:7]
.LBB0_818:
	s_or_b64 exec, exec, s[10:11]
	ds_read_b128 v[26:29], v128 offset:1040
	s_or_b32 s6, s31, s25
	s_ashr_i32 s7, s6, 31
	s_lshl_b64 s[10:11], s[6:7], 11
	s_add_u32 s10, s17, s10
	s_waitcnt vmcnt(7) lgkmcnt(0)
	v_pk_add_f32 v[22:23], v[22:23], v[26:27]
	v_pk_add_f32 v[24:25], v[24:25], v[28:29]
	v_cvt_pk_bf16_f32 v26, v22, v23
	v_mul_f32_e32 v23, v23, v23
	v_fmac_f32_e32 v23, v22, v22
	v_mul_f32_e32 v22, v25, v25
	v_fmac_f32_e32 v22, v24, v24
	v_add_f32_e32 v22, v23, v22
	s_addc_u32 s11, s18, s11
	s_add_u32 s10, s10, s4
	v_add_f32_dpp v22, v22, v22 quad_perm:[1,0,3,2] row_mask:0xf bank_mask:0xf bound_ctrl:1
	s_addc_u32 s11, s11, s5
	v_cvt_pk_bf16_f32 v27, v24, v25
	v_add_f32_dpp v22, v22, v22 quad_perm:[2,3,0,1] row_mask:0xf bank_mask:0xf bound_ctrl:1
	v_lshl_add_u64 v[28:29], v[130:131], 1, s[10:11]
	global_store_dwordx2 v[28:29], v[26:27], off sc1
	v_add_f32_dpp v22, v22, v22 row_half_mirror row_mask:0xf bank_mask:0xf bound_ctrl:1
	s_nop 1
	v_add_f32_dpp v22, v22, v22 row_mirror row_mask:0xf bank_mask:0xf bound_ctrl:1
	v_mov_b32_e32 v23, v22
	s_nop 1
	v_permlane16_swap_b32_e32 v22, v23
	v_add_f32_e32 v22, v22, v23
	v_mov_b32_e32 v23, v22
	s_nop 1
	v_permlane32_swap_b32_e32 v22, v23
	s_and_saveexec_b64 s[10:11], vcc
	s_cbranch_execz .LBB0_820
	s_lshl_b64 s[6:7], s[6:7], 4
	s_add_u32 s12, s15, s6
	s_addc_u32 s13, s16, s7
	s_lshl_b64 s[6:7], s[8:9], 2
	s_add_u32 s6, s12, s6
	s_addc_u32 s7, s13, s7
	v_mov_b32_e32 v24, 0
	v_add_f32_e32 v22, v22, v23
	global_store_dword v24, v22, s[6:7]
.LBB0_820:
	s_or_b64 exec, exec, s[10:11]
	ds_read_b128 v[22:25], v128 offset:2080
	s_or_b32 s6, s31, s26
	s_ashr_i32 s7, s6, 31
	s_lshl_b64 s[10:11], s[6:7], 11
	s_add_u32 s10, s17, s10
	s_waitcnt vmcnt(7) lgkmcnt(0)
	v_pk_add_f32 v[18:19], v[18:19], v[22:23]
	v_pk_add_f32 v[20:21], v[20:21], v[24:25]
	v_cvt_pk_bf16_f32 v22, v18, v19
	v_mul_f32_e32 v19, v19, v19
	v_fmac_f32_e32 v19, v18, v18
	v_mul_f32_e32 v18, v21, v21
	v_fmac_f32_e32 v18, v20, v20
	v_add_f32_e32 v18, v19, v18
	s_addc_u32 s11, s18, s11
	s_add_u32 s10, s10, s4
	v_add_f32_dpp v18, v18, v18 quad_perm:[1,0,3,2] row_mask:0xf bank_mask:0xf bound_ctrl:1
	s_addc_u32 s11, s11, s5
	v_cvt_pk_bf16_f32 v23, v20, v21
	v_add_f32_dpp v18, v18, v18 quad_perm:[2,3,0,1] row_mask:0xf bank_mask:0xf bound_ctrl:1
	v_lshl_add_u64 v[24:25], v[130:131], 1, s[10:11]
	global_store_dwordx2 v[24:25], v[22:23], off sc1
	v_add_f32_dpp v18, v18, v18 row_half_mirror row_mask:0xf bank_mask:0xf bound_ctrl:1
	s_nop 1
	v_add_f32_dpp v18, v18, v18 row_mirror row_mask:0xf bank_mask:0xf bound_ctrl:1
	v_mov_b32_e32 v19, v18
	s_nop 1
	v_permlane16_swap_b32_e32 v18, v19
	v_add_f32_e32 v18, v18, v19
	v_mov_b32_e32 v19, v18
	s_nop 1
	v_permlane32_swap_b32_e32 v18, v19
	s_and_saveexec_b64 s[10:11], vcc
	s_cbranch_execz .LBB0_822
	s_lshl_b64 s[6:7], s[6:7], 4
	s_add_u32 s12, s15, s6
	s_addc_u32 s13, s16, s7
	s_lshl_b64 s[6:7], s[8:9], 2
	s_add_u32 s6, s12, s6
	s_addc_u32 s7, s13, s7
	v_mov_b32_e32 v20, 0
	v_add_f32_e32 v18, v18, v19
	global_store_dword v20, v18, s[6:7]
.LBB0_822:
	s_or_b64 exec, exec, s[10:11]
	ds_read_b128 v[18:21], v128 offset:3120
	s_or_b32 s6, s31, s27
	s_ashr_i32 s7, s6, 31
	s_lshl_b64 s[10:11], s[6:7], 11
	s_add_u32 s10, s17, s10
	s_waitcnt vmcnt(7) lgkmcnt(0)
	v_pk_add_f32 v[14:15], v[14:15], v[18:19]
	v_pk_add_f32 v[16:17], v[16:17], v[20:21]
	v_cvt_pk_bf16_f32 v18, v14, v15
	v_mul_f32_e32 v15, v15, v15
	v_fmac_f32_e32 v15, v14, v14
	v_mul_f32_e32 v14, v17, v17
	v_fmac_f32_e32 v14, v16, v16
	v_add_f32_e32 v14, v15, v14
	s_addc_u32 s11, s18, s11
	s_add_u32 s10, s10, s4
	v_add_f32_dpp v14, v14, v14 quad_perm:[1,0,3,2] row_mask:0xf bank_mask:0xf bound_ctrl:1
	s_addc_u32 s11, s11, s5
	v_cvt_pk_bf16_f32 v19, v16, v17
	v_add_f32_dpp v14, v14, v14 quad_perm:[2,3,0,1] row_mask:0xf bank_mask:0xf bound_ctrl:1
	v_lshl_add_u64 v[20:21], v[130:131], 1, s[10:11]
	global_store_dwordx2 v[20:21], v[18:19], off sc1
	v_add_f32_dpp v14, v14, v14 row_half_mirror row_mask:0xf bank_mask:0xf bound_ctrl:1
	s_nop 1
	v_add_f32_dpp v14, v14, v14 row_mirror row_mask:0xf bank_mask:0xf bound_ctrl:1
	v_mov_b32_e32 v15, v14
	s_nop 1
	v_permlane16_swap_b32_e32 v14, v15
	v_add_f32_e32 v14, v14, v15
	v_mov_b32_e32 v15, v14
	s_nop 1
	v_permlane32_swap_b32_e32 v14, v15
	s_and_saveexec_b64 s[10:11], vcc
	s_cbranch_execz .LBB0_824
	s_lshl_b64 s[6:7], s[6:7], 4
	s_add_u32 s12, s15, s6
	s_addc_u32 s13, s16, s7
	s_lshl_b64 s[6:7], s[8:9], 2
	s_add_u32 s6, s12, s6
	s_addc_u32 s7, s13, s7
	v_mov_b32_e32 v16, 0
	v_add_f32_e32 v14, v14, v15
	global_store_dword v16, v14, s[6:7]
.LBB0_824:
	s_or_b64 exec, exec, s[10:11]
	ds_read_b128 v[14:17], v128 offset:4160
	s_or_b32 s6, s31, s28
	s_ashr_i32 s7, s6, 31
	s_lshl_b64 s[10:11], s[6:7], 11
	s_add_u32 s10, s17, s10
	s_waitcnt vmcnt(7) lgkmcnt(0)
	v_pk_add_f32 v[10:11], v[10:11], v[14:15]
	v_pk_add_f32 v[12:13], v[12:13], v[16:17]
	v_cvt_pk_bf16_f32 v14, v10, v11
	v_mul_f32_e32 v11, v11, v11
	v_fmac_f32_e32 v11, v10, v10
	v_mul_f32_e32 v10, v13, v13
	v_fmac_f32_e32 v10, v12, v12
	v_add_f32_e32 v10, v11, v10
	s_addc_u32 s11, s18, s11
	s_add_u32 s10, s10, s4
	v_add_f32_dpp v10, v10, v10 quad_perm:[1,0,3,2] row_mask:0xf bank_mask:0xf bound_ctrl:1
	s_addc_u32 s11, s11, s5
	v_cvt_pk_bf16_f32 v15, v12, v13
	v_add_f32_dpp v10, v10, v10 quad_perm:[2,3,0,1] row_mask:0xf bank_mask:0xf bound_ctrl:1
	v_lshl_add_u64 v[16:17], v[130:131], 1, s[10:11]
	global_store_dwordx2 v[16:17], v[14:15], off sc1
	v_add_f32_dpp v10, v10, v10 row_half_mirror row_mask:0xf bank_mask:0xf bound_ctrl:1
	s_nop 1
	v_add_f32_dpp v10, v10, v10 row_mirror row_mask:0xf bank_mask:0xf bound_ctrl:1
	v_mov_b32_e32 v11, v10
	s_nop 1
	v_permlane16_swap_b32_e32 v10, v11
	v_add_f32_e32 v10, v10, v11
	v_mov_b32_e32 v11, v10
	s_nop 1
	v_permlane32_swap_b32_e32 v10, v11
	s_and_saveexec_b64 s[10:11], vcc
	s_cbranch_execz .LBB0_826
	s_lshl_b64 s[6:7], s[6:7], 4
	s_add_u32 s12, s15, s6
	s_addc_u32 s13, s16, s7
	s_lshl_b64 s[6:7], s[8:9], 2
	s_add_u32 s6, s12, s6
	s_addc_u32 s7, s13, s7
	v_mov_b32_e32 v12, 0
	v_add_f32_e32 v10, v10, v11
	global_store_dword v12, v10, s[6:7]
.LBB0_826:
	s_or_b64 exec, exec, s[10:11]
	ds_read_b128 v[10:13], v128 offset:5200
	s_or_b32 s6, s31, s29
	s_ashr_i32 s7, s6, 31
	s_lshl_b64 s[10:11], s[6:7], 11
	s_add_u32 s10, s17, s10
	s_waitcnt vmcnt(7) lgkmcnt(0)
	v_pk_add_f32 v[6:7], v[6:7], v[10:11]
	v_pk_add_f32 v[8:9], v[8:9], v[12:13]
	v_cvt_pk_bf16_f32 v10, v6, v7
	v_mul_f32_e32 v7, v7, v7
	v_fmac_f32_e32 v7, v6, v6
	v_mul_f32_e32 v6, v9, v9
	v_fmac_f32_e32 v6, v8, v8
	v_add_f32_e32 v6, v7, v6
	s_addc_u32 s11, s18, s11
	s_add_u32 s10, s10, s4
	v_add_f32_dpp v6, v6, v6 quad_perm:[1,0,3,2] row_mask:0xf bank_mask:0xf bound_ctrl:1
	s_addc_u32 s11, s11, s5
	v_cvt_pk_bf16_f32 v11, v8, v9
	v_add_f32_dpp v6, v6, v6 quad_perm:[2,3,0,1] row_mask:0xf bank_mask:0xf bound_ctrl:1
	v_lshl_add_u64 v[12:13], v[130:131], 1, s[10:11]
	global_store_dwordx2 v[12:13], v[10:11], off sc1
	v_add_f32_dpp v6, v6, v6 row_half_mirror row_mask:0xf bank_mask:0xf bound_ctrl:1
	s_nop 1
	v_add_f32_dpp v6, v6, v6 row_mirror row_mask:0xf bank_mask:0xf bound_ctrl:1
	v_mov_b32_e32 v7, v6
	s_nop 1
	v_permlane16_swap_b32_e32 v6, v7
	v_add_f32_e32 v6, v6, v7
	v_mov_b32_e32 v7, v6
	s_nop 1
	v_permlane32_swap_b32_e32 v6, v7
	s_and_saveexec_b64 s[10:11], vcc
	s_cbranch_execz .LBB0_828
	s_lshl_b64 s[6:7], s[6:7], 4
	s_add_u32 s12, s15, s6
	s_addc_u32 s13, s16, s7
	s_lshl_b64 s[6:7], s[8:9], 2
	s_add_u32 s6, s12, s6
	s_addc_u32 s7, s13, s7
	v_mov_b32_e32 v8, 0
	v_add_f32_e32 v6, v6, v7
	global_store_dword v8, v6, s[6:7]
.LBB0_828:
	s_or_b64 exec, exec, s[10:11]
	ds_read_b128 v[6:9], v128 offset:6240
	s_or_b32 s6, s31, s30
	s_ashr_i32 s7, s6, 31
	s_lshl_b64 s[10:11], s[6:7], 11
	s_add_u32 s10, s17, s10
	s_waitcnt vmcnt(7) lgkmcnt(0)
	v_pk_add_f32 v[2:3], v[2:3], v[6:7]
	v_pk_add_f32 v[4:5], v[4:5], v[8:9]
	v_cvt_pk_bf16_f32 v6, v2, v3
	v_mul_f32_e32 v3, v3, v3
	v_fmac_f32_e32 v3, v2, v2
	v_mul_f32_e32 v2, v5, v5
	v_fmac_f32_e32 v2, v4, v4
	v_add_f32_e32 v2, v3, v2
	s_addc_u32 s11, s18, s11
	s_add_u32 s4, s10, s4
	v_add_f32_dpp v2, v2, v2 quad_perm:[1,0,3,2] row_mask:0xf bank_mask:0xf bound_ctrl:1
	s_addc_u32 s5, s11, s5
	v_cvt_pk_bf16_f32 v7, v4, v5
	v_add_f32_dpp v2, v2, v2 quad_perm:[2,3,0,1] row_mask:0xf bank_mask:0xf bound_ctrl:1
	v_lshl_add_u64 v[8:9], v[130:131], 1, s[4:5]
	global_store_dwordx2 v[8:9], v[6:7], off sc1
	v_add_f32_dpp v2, v2, v2 row_half_mirror row_mask:0xf bank_mask:0xf bound_ctrl:1
	s_nop 1
	v_add_f32_dpp v2, v2, v2 row_mirror row_mask:0xf bank_mask:0xf bound_ctrl:1
	v_mov_b32_e32 v3, v2
	s_nop 1
	v_permlane16_swap_b32_e32 v2, v3
	v_add_f32_e32 v2, v2, v3
	v_mov_b32_e32 v3, v2
	s_nop 1
	v_permlane32_swap_b32_e32 v2, v3
	s_and_saveexec_b64 s[4:5], vcc
	s_cbranch_execz .LBB0_830
	s_lshl_b64 s[6:7], s[6:7], 4
	s_add_u32 s10, s15, s6
	s_addc_u32 s11, s16, s7
	s_lshl_b64 s[6:7], s[8:9], 2
	s_add_u32 s6, s10, s6
	s_addc_u32 s7, s11, s7
	v_mov_b32_e32 v4, 0
	v_add_f32_e32 v2, v2, v3
	global_store_dword v4, v2, s[6:7]
